# band attention: far-tile constant bias folded into the running-max and the subtracted offset (softmax runs on the MFMA result registers directly; near tiles add their gathered bias in place), removing
# speedup vs baseline: 1.0074x; 1.0074x over previous
.Lbg_tail:
	s_waitcnt lgkmcnt(14)
	v_pk_add_f32 v[64:65], v[64:65], v[16:17]
	v_pk_add_f32 v[62:63], v[62:63], v[130:131]
	v_pk_add_f32 v[60:61], v[60:61], v[14:15]
	v_pk_add_f32 v[58:59], v[58:59], v[12:13]
	v_pk_add_f32 v[56:57], v[56:57], v[10:11]
	v_pk_add_f32 v[54:55], v[54:55], v[8:9]
	v_pk_add_f32 v[52:53], v[52:53], v[6:7]
	v_pk_add_f32 v[50:51], v[50:51], v[4:5]
	s_waitcnt lgkmcnt(0)
	v_pk_add_f32 v[80:81], v[80:81], v[184:185]
	v_pk_add_f32 v[78:79], v[78:79], v[182:183]
	v_pk_add_f32 v[76:77], v[76:77], v[180:181]
	v_pk_add_f32 v[74:75], v[74:75], v[178:179]
	v_pk_add_f32 v[72:73], v[72:73], v[176:177]
	v_pk_add_f32 v[70:71], v[70:71], v[174:175]
	v_pk_add_f32 v[68:69], v[68:69], v[132:133]
	v_pk_add_f32 v[66:67], v[66:67], v[136:137]
	v_mov_b32_e32 v223, 0
	s_mov_b64 s[60:61], 0
.LBB0_457:
	s_andn2_b64 vcc, exec, s[60:61]
	s_cbranch_vccnz .LBB0_459
	v_mov_b32_e32 v223, v220
.LBB0_459:
	ds_read_b64_tr_b16 v[188:189], v153 offset:9216
	ds_read_b64_tr_b16 v[190:191], v153 offset:9984
	ds_read_b64_tr_b16 v[192:193], v153 offset:9280
	ds_read_b64_tr_b16 v[194:195], v153 offset:10048
	ds_read_b64_tr_b16 v[196:197], v153 offset:12288
	ds_read_b64_tr_b16 v[198:199], v153 offset:13056
	ds_read_b64_tr_b16 v[200:201], v153 offset:12352
	ds_read_b64_tr_b16 v[202:203], v153 offset:13120
	ds_read_b64_tr_b16 v[204:205], v153 offset:15360
	ds_read_b64_tr_b16 v[206:207], v153 offset:16128
	ds_read_b64_tr_b16 v[208:209], v153 offset:15424
	ds_read_b64_tr_b16 v[210:211], v153 offset:16192
	ds_read_b64_tr_b16 v[212:213], v153 offset:18432
	ds_read_b64_tr_b16 v[214:215], v153 offset:19200
	ds_read_b64_tr_b16 v[216:217], v153 offset:18496
	ds_read_b64_tr_b16 v[218:219], v153 offset:19264
	s_nop 0
	v_max_f32_e32 v2, v51, v51
	s_nop 2
	v_max_f32_e32 v225, v50, v50
	v_max_f32_e32 v2, v225, v2
	v_max3_f32 v2, v2, v52, v53
	v_max3_f32 v2, v2, v54, v55
	v_max3_f32 v2, v2, v56, v57
	v_max3_f32 v2, v2, v58, v59
	v_max3_f32 v2, v2, v60, v61
	v_max3_f32 v2, v2, v62, v63
	v_max3_f32 v2, v2, v64, v65
	v_max3_f32 v2, v2, v66, v67
	v_max3_f32 v2, v2, v68, v69
	v_max3_f32 v2, v2, v70, v71
	v_max3_f32 v2, v2, v72, v73
	v_max3_f32 v2, v2, v74, v75
	v_max3_f32 v2, v2, v76, v77
	v_max3_f32 v2, v2, v78, v79
	v_max3_f32 v2, v2, v80, v81
	v_add_f32_e32 v2, v2, v223
	v_mov_b32_e32 v225, v2
	s_nop 1
	v_permlane32_swap_b32_e32 v225, v2
	v_max3_f32 v224, v173, v2, v225
	v_add_f32_e32 v2, 0x41000000, v173
	v_cmp_gt_f32_e32 vcc, v224, v2
	s_nop 1
	v_cndmask_b32_e32 v224, v173, v224, vcc
	v_sub_f32_e32 v2, v173, v224
	v_exp_f32_e32 v2, v2
	s_nop 0
	v_cmp_neq_f32_e32 vcc, 1.0, v2
	s_cbranch_vccz .LBB0_461
	v_mul_f32_e32 v48, v2, v48
	v_mul_f32_e32 v49, v2, v49
	v_mul_f32_e32 v46, v2, v46
	v_mul_f32_e32 v47, v2, v47
	v_mul_f32_e32 v44, v2, v44
	v_mul_f32_e32 v45, v2, v45
	v_mul_f32_e32 v42, v2, v42
	v_mul_f32_e32 v43, v2, v43
	v_mul_f32_e32 v40, v2, v40
	v_mul_f32_e32 v41, v2, v41
	v_mul_f32_e32 v38, v2, v38
	v_mul_f32_e32 v39, v2, v39
	v_mul_f32_e32 v36, v2, v36
	v_mul_f32_e32 v37, v2, v37
	v_mul_f32_e32 v34, v2, v34
	v_mul_f32_e32 v35, v2, v35
	v_mul_f32_e32 v32, v2, v32
	v_mul_f32_e32 v33, v2, v33
	v_mul_f32_e32 v30, v2, v30
	v_mul_f32_e32 v31, v2, v31
	v_mul_f32_e32 v28, v2, v28
	v_mul_f32_e32 v29, v2, v29
	v_mul_f32_e32 v26, v2, v26
	v_mul_f32_e32 v27, v2, v27
	v_mul_f32_e32 v24, v2, v24
	v_mul_f32_e32 v25, v2, v25
	v_mul_f32_e32 v22, v2, v22
	v_mul_f32_e32 v23, v2, v23
	v_mul_f32_e32 v20, v2, v20
	v_mul_f32_e32 v21, v2, v21
	v_mul_f32_e32 v18, v2, v18
	v_mul_f32_e32 v19, v2, v19
.LBB0_461:
	v_sub_f32_e32 v225, v224, v223
	v_pk_add_f32 v[50:51], v[50:51], v[224:225] op_sel:[0,1] op_sel_hi:[1,1] neg_lo:[0,1] neg_hi:[0,1]
	v_pk_add_f32 v[52:53], v[52:53], v[224:225] op_sel:[0,1] op_sel_hi:[1,1] neg_lo:[0,1] neg_hi:[0,1]
	v_pk_add_f32 v[54:55], v[54:55], v[224:225] op_sel:[0,1] op_sel_hi:[1,1] neg_lo:[0,1] neg_hi:[0,1]
	v_pk_add_f32 v[56:57], v[56:57], v[224:225] op_sel:[0,1] op_sel_hi:[1,1] neg_lo:[0,1] neg_hi:[0,1]
	v_pk_add_f32 v[58:59], v[58:59], v[224:225] op_sel:[0,1] op_sel_hi:[1,1] neg_lo:[0,1] neg_hi:[0,1]
	v_pk_add_f32 v[60:61], v[60:61], v[224:225] op_sel:[0,1] op_sel_hi:[1,1] neg_lo:[0,1] neg_hi:[0,1]
	v_pk_add_f32 v[62:63], v[62:63], v[224:225] op_sel:[0,1] op_sel_hi:[1,1] neg_lo:[0,1] neg_hi:[0,1]
	v_pk_add_f32 v[64:65], v[64:65], v[224:225] op_sel:[0,1] op_sel_hi:[1,1] neg_lo:[0,1] neg_hi:[0,1]
	v_pk_add_f32 v[66:67], v[66:67], v[224:225] op_sel:[0,1] op_sel_hi:[1,1] neg_lo:[0,1] neg_hi:[0,1]
	v_pk_add_f32 v[68:69], v[68:69], v[224:225] op_sel:[0,1] op_sel_hi:[1,1] neg_lo:[0,1] neg_hi:[0,1]
	v_pk_add_f32 v[70:71], v[70:71], v[224:225] op_sel:[0,1] op_sel_hi:[1,1] neg_lo:[0,1] neg_hi:[0,1]
	v_pk_add_f32 v[72:73], v[72:73], v[224:225] op_sel:[0,1] op_sel_hi:[1,1] neg_lo:[0,1] neg_hi:[0,1]
	v_pk_add_f32 v[74:75], v[74:75], v[224:225] op_sel:[0,1] op_sel_hi:[1,1] neg_lo:[0,1] neg_hi:[0,1]
	v_pk_add_f32 v[76:77], v[76:77], v[224:225] op_sel:[0,1] op_sel_hi:[1,1] neg_lo:[0,1] neg_hi:[0,1]
	v_pk_add_f32 v[78:79], v[78:79], v[224:225] op_sel:[0,1] op_sel_hi:[1,1] neg_lo:[0,1] neg_hi:[0,1]
	v_pk_add_f32 v[80:81], v[80:81], v[224:225] op_sel:[0,1] op_sel_hi:[1,1] neg_lo:[0,1] neg_hi:[0,1]
	v_exp_f32_e32 v4, v50
	v_exp_f32_e32 v5, v51
	v_exp_f32_e32 v6, v52
	v_exp_f32_e32 v7, v53
	v_exp_f32_e32 v8, v54
	v_exp_f32_e32 v9, v55
	v_pk_add_f32 v[226:227], v[4:5], v[6:7]
	v_exp_f32_e32 v10, v56
	v_exp_f32_e32 v11, v57
	v_pk_add_f32 v[226:227], v[226:227], v[8:9]
	v_exp_f32_e32 v12, v58
	v_exp_f32_e32 v13, v59
	v_pk_add_f32 v[226:227], v[226:227], v[10:11]
	v_exp_f32_e32 v14, v60
	v_exp_f32_e32 v15, v61
	v_pk_add_f32 v[226:227], v[226:227], v[12:13]
	v_exp_f32_e32 v16, v62
	v_exp_f32_e32 v17, v63
	v_pk_add_f32 v[226:227], v[226:227], v[14:15]
	v_exp_f32_e32 v130, v64
	v_exp_f32_e32 v131, v65
	v_pk_add_f32 v[226:227], v[226:227], v[16:17]
	v_exp_f32_e32 v132, v66
	v_exp_f32_e32 v133, v67
	v_pk_add_f32 v[226:227], v[226:227], v[130:131]
	v_exp_f32_e32 v134, v68
	v_exp_f32_e32 v135, v69
	v_pk_add_f32 v[226:227], v[226:227], v[132:133]
	v_exp_f32_e32 v136, v70
	v_exp_f32_e32 v137, v71
	v_pk_add_f32 v[226:227], v[226:227], v[134:135]
	v_exp_f32_e32 v138, v72
	v_exp_f32_e32 v139, v73
	v_pk_add_f32 v[226:227], v[226:227], v[136:137]
	v_exp_f32_e32 v140, v74
	v_exp_f32_e32 v141, v75
	v_pk_add_f32 v[226:227], v[226:227], v[138:139]
	v_exp_f32_e32 v142, v76
	v_exp_f32_e32 v143, v77
	v_pk_add_f32 v[226:227], v[226:227], v[140:141]
	v_exp_f32_e32 v144, v78
	v_exp_f32_e32 v145, v79
	v_pk_add_f32 v[226:227], v[226:227], v[142:143]
	v_exp_f32_e32 v146, v80
	v_exp_f32_e32 v147, v81
	v_pk_add_f32 v[226:227], v[226:227], v[144:145]
	s_nop 0
	v_pk_add_f32 v[226:227], v[226:227], v[146:147]
	v_add_f32_e32 v226, v226, v227
	v_cvt_pk_bf16_f32 v4, v4, v5
	v_cvt_pk_bf16_f32 v5, v6, v7
	v_cvt_pk_bf16_f32 v6, v8, v9
	v_cvt_pk_bf16_f32 v7, v10, v11
	v_cvt_pk_bf16_f32 v8, v12, v13
	v_cvt_pk_bf16_f32 v9, v14, v15
	v_cvt_pk_bf16_f32 v10, v16, v17
	v_cvt_pk_bf16_f32 v11, v130, v131
	v_fmac_f32_e32 v226, v172, v2
	v_cvt_pk_bf16_f32 v12, v132, v133
	v_cvt_pk_bf16_f32 v13, v134, v135
	v_cvt_pk_bf16_f32 v14, v136, v137
	v_cvt_pk_bf16_f32 v15, v138, v139
	v_cvt_pk_bf16_f32 v68, v140, v141
	v_cvt_pk_bf16_f32 v69, v142, v143
	v_cvt_pk_bf16_f32 v70, v144, v145
	v_cvt_pk_bf16_f32 v71, v146, v147
	s_waitcnt lgkmcnt(0)
	v_mfma_f32_32x32x16_bf16 v[34:49], v[188:191], v[4:7], v[34:49]
	v_mfma_f32_32x32x16_bf16 v[18:33], v[192:195], v[4:7], v[18:33]
	v_mfma_f32_32x32x16_bf16 v[34:49], v[196:199], v[8:11], v[34:49]
	v_mfma_f32_32x32x16_bf16 v[18:33], v[200:203], v[8:11], v[18:33]
	v_mfma_f32_32x32x16_bf16 v[34:49], v[204:207], v[12:15], v[34:49]
	v_mfma_f32_32x32x16_bf16 v[18:33], v[208:211], v[12:15], v[18:33]
	v_mfma_f32_32x32x16_bf16 v[34:49], v[212:215], v[68:71], v[34:49]
	v_mfma_f32_32x32x16_bf16 v[18:33], v[216:219], v[68:71], v[18:33]
	v_mov_b32_e32 v172, v226
	s_branch .LBB0_463
.LBB0_462:
	v_mov_b32_e32 v224, v173
.LBB0_463:
	s_add_i32 s23, s23, 1
	v_subrev_u32_e32 v119, 64, v119
	s_add_i32 s64, s64, -1
	v_add_u32_e32 v128, 64, v128
	s_and_b64 vcc, exec, s[26:27]
	s_cbranch_vccnz .LBB0_466
	v_mov_b32_e32 v173, v224
	s_branch .LBB0_452
